# stack on the combination build: phase B invariant hoist, row-sum without the 0+ add, window block list via v_readlane, fragment reads issued right after the barrier
# baseline (speedup 1.0000x reference)
; DI void nsa_ldsfrag(KVFrag& f, const unsigned char* slot, int qi, int quad) {
;   const int krow = 8 * (qi >> 2) + (qi & 3);
; #pragma unroll
;   for (int a = 0; a < 2; ++a) { const unsigned char* kp = slot + (krow + 4 * a) * NSA_KROW + quad * 16; f.k[a][0] = mk8(*(const u32x4*)kp); f.k[a][1] = mk8(*(const u32x4*)(kp + 64)); }
; #pragma unroll
;   for (int dt = 0; dt < 4; ++dt) f.v[dt] = mk8(*(const u32x4*)(slot + 32 * NSA_KROW + (dt * 16 + qi) * NSA_VROW + quad * 16));
; }
; template <int MODE>
; DI void nsa_branch(const bf16_t* __restrict__ Kb, const bf16_t* __restrict__ Vtb, unsigned char* lds, int nb, int t, int cur, unsigned selmask, unsigned umall,
;                    const bf16x8 (&qf)[4][2], f32x4 (&O)[4][4], float (&m)[4], float (&l)[4], bool online) {
;     ...
;   for (int n = 0; n < N; n += 2) {
;     const int j = blist[n >> 1];
;     const bool won = MODE == 0 ? ((umall >> j) & 1u) != 0 : (j >= cur - 8 && j <= cur);
;     const bool bit = (selmask >> j) & 1u;
;     ra = *(const u32x4*)(gsrc + (long)kbof(min(n + 2, N - 2)) * gmul);
;     if (won) { KVFrag f; nsa_ldsfrag(f, slot0, qi, quad); nsa_chunk<MODE>(f, j * 64, t, bit, qf, O, m, l, quad, online); }
.LBB0_727:
	ds_read_b128 v[136:139], v176
	ds_read_b128 v[140:143], v230
	ds_read_b128 v[144:147], v176 offset:512
	ds_read_b128 v[132:135], v230 offset:512
	ds_read_b128 v[128:131], v177
	ds_read_b128 v[124:127], v177 offset:1024
	ds_read_b128 v[120:123], v177 offset:2048
	s_sub_u32 s58, s56, 0x14c20
	s_lshr_b32 s58, s58, 2
	v_readlane_b32 s0, v216, s58
	s_nop 1
	v_mov_b32_e32 v181, s0
	s_lshl_b32 s10, 1, s0
	s_and_b32 s11, s10, s42
	s_cmp_lg_u32 s11, 0
	s_cselect_b64 s[0:1], -1, 0
	s_add_i32 s57, s54, -1
	s_min_i32 s12, s57, s43
	s_lshr_b32 s12, s12, 1
	v_readlane_b32 s58, v216, s12
	v_and_b32_e32 v116, s10, v171
	v_cmp_ne_u32_e64 s[12:13], 0, v116
	v_cndmask_b32_e64 v116, 0, 1, s[8:9]
	s_lshl_b32 s58, s58, 6
	s_ashr_i32 s59, s58, 31
	s_lshl_b64 s[58:59], s[58:59], 7
	s_cmp_eq_u32 s11, 0
	v_lshl_add_u64 v[112:113], v[168:169], 0, s[58:59]
	global_load_dwordx4 v[112:115], v[112:113], off
	v_cmp_ne_u32_e64 s[10:11], 1, v116
	s_cbranch_scc1 .LBB0_737
	s_and_b64 vcc, exec, s[10:11]
	s_cbranch_vccz .Lmy_nf_s1
	v_readfirstlane_b32 s58, v181
	v_readfirstlane_b32 s59, v160
	s_lshl_b32 s58, s58, 6
	s_add_u32 s60, s58, 63
	s_cmp_le_i32 s60, s59
	s_cbranch_scc0 .Lmy_nf_s1
	ds_read_b128 v[116:119], v177 offset:3072
	v_mov_b32_e32 v226, 0xff800000
	v_cndmask_b32_e64 v218, v226, 0, s[12:13]
	v_cndmask_b32_e64 v219, v226, 0, s[12:13]
	v_cndmask_b32_e64 v220, v226, 0, s[12:13]
	v_cndmask_b32_e64 v221, v226, 0, s[12:13]
	s_branch .Lmy_full_s1
.Lmy_nf_s1:
	v_lshl_or_b32 v182, v181, 6, v173
	v_cmp_le_i32_e32 vcc, v182, v160
	s_and_b64 s[16:17], s[12:13], vcc
	v_cmp_lt_i32_e32 vcc, v182, v160
	v_or_b32_e32 v148, 2, v182
	s_and_b64 s[18:19], s[12:13], vcc
	v_cmp_le_i32_e32 vcc, v148, v160
	v_or_b32_e32 v148, 3, v182
	s_and_b64 s[44:45], s[12:13], vcc
	v_cmp_le_i32_e32 vcc, v148, v160
	v_or_b32_e32 v148, 4, v182
	ds_read_b128 v[116:119], v177 offset:3072
	s_and_b64 s[46:47], s[12:13], vcc
	v_cmp_le_i32_e32 vcc, v148, v160
	v_or_b32_e32 v152, 5, v182
	s_and_b64 s[14:15], s[12:13], vcc
	v_cmp_le_i32_e32 vcc, v152, v160
	v_or_b32_e32 v183, 6, v182
	s_and_b64 s[48:49], s[12:13], vcc
	v_cmp_le_i32_e32 vcc, v183, v160
	v_or_b32_e32 v182, 7, v182
	s_and_b64 s[50:51], s[12:13], vcc
	v_cmp_le_i32_e32 vcc, v182, v160
	s_and_b64 s[52:53], s[12:13], vcc
	s_and_b64 vcc, exec, s[10:11]
	v_mov_b32_e32 v226, 0xff800000
	v_cndmask_b32_e64 v218, v226, 0, s[16:17]
	v_cndmask_b32_e64 v219, v226, 0, s[18:19]
	v_cndmask_b32_e64 v220, v226, 0, s[44:45]
	v_cndmask_b32_e64 v221, v226, 0, s[46:47]
	v_cndmask_b32_e64 v222, v226, 0, s[14:15]
	v_cndmask_b32_e64 v223, v226, 0, s[48:49]
	v_cndmask_b32_e64 v224, v226, 0, s[50:51]
	v_cndmask_b32_e64 v225, v226, 0, s[52:53]
	s_nop 1
	s_cbranch_vccnz .Lmy_fast_s1
	s_waitcnt lgkmcnt(7)
	v_mfma_f32_16x16x32_bf16 v[148:151], v[136:139], v[8:11], v[218:221]
	s_waitcnt lgkmcnt(6)
	v_mfma_f32_16x16x32_bf16 v[152:155], v[140:143], v[12:15], v[148:151]
	s_waitcnt lgkmcnt(5)
	v_mfma_f32_16x16x32_bf16 v[148:151], v[144:147], v[8:11], v[222:225]
	s_waitcnt lgkmcnt(4)
	v_mfma_f32_16x16x32_bf16 v[148:151], v[132:135], v[12:15], v[148:151]
	s_nop 7
	s_cbranch_vccnz .LBB0_730
	v_mul_f32_e32 v182, 0x3e38aa3b, v152
	v_max_f32_e32 v182, 0xf149f2ca, v182
	v_cndmask_b32_e64 v182, v232, v182, s[16:17]
	v_mul_f32_e32 v183, 0x3e38aa3b, v153
	v_max_f32_e32 v183, v182, v183
	v_cndmask_b32_e64 v182, v182, v183, s[18:19]
	v_mul_f32_e32 v183, 0x3e38aa3b, v154
	v_max_f32_e32 v183, v182, v183
	v_cndmask_b32_e64 v182, v182, v183, s[44:45]
	v_mul_f32_e32 v183, 0x3e38aa3b, v155
	v_max_f32_e32 v183, v182, v183
	v_cndmask_b32_e64 v182, v182, v183, s[46:47]
	v_mul_f32_e32 v183, 0x3e38aa3b, v148
	v_max_f32_e32 v183, v182, v183
	v_cndmask_b32_e64 v182, v182, v183, s[14:15]
	v_mul_f32_e32 v183, 0x3e38aa3b, v149
	v_max_f32_e32 v184, v182, v182
	v_max_f32_e32 v183, v184, v183
	v_cndmask_b32_e64 v182, v182, v183, s[48:49]
	v_mul_f32_e32 v183, 0x3e38aa3b, v150
	v_max_f32_e32 v184, v182, v182
	v_max_f32_e32 v183, v184, v183
	v_cndmask_b32_e64 v182, v182, v183, s[50:51]
	v_mul_f32_e32 v183, 0x3e38aa3b, v151
	v_max_f32_e32 v184, v182, v182
	v_max_f32_e32 v183, v184, v183
	v_cndmask_b32_e64 v182, v182, v183, s[52:53]
	ds_bpermute_b32 v183, v175, v182
	v_max_f32_e32 v182, v182, v182
	s_waitcnt lgkmcnt(0)
	v_max_f32_e32 v183, v183, v183
	v_max_f32_e32 v182, v182, v183
	ds_bpermute_b32 v183, v159, v182
	s_waitcnt lgkmcnt(0)
	v_max3_f32 v183, v3, v182, v183
	v_sub_f32_e32 v3, v3, v183
	v_exp_f32_e32 v182, v3
	v_mov_b32_e32 v3, v183
	v_mul_f32_e32 v167, v167, v182
	v_pk_mul_f32 v[106:107], v[106:107], v[182:183] op_sel_hi:[1,0]
	v_pk_mul_f32 v[104:105], v[104:105], v[182:183] op_sel_hi:[1,0]
	v_pk_mul_f32 v[102:103], v[102:103], v[182:183] op_sel_hi:[1,0]
	v_pk_mul_f32 v[100:101], v[100:101], v[182:183] op_sel_hi:[1,0]
	v_pk_mul_f32 v[98:99], v[98:99], v[182:183] op_sel_hi:[1,0]
	v_pk_mul_f32 v[96:97], v[96:97], v[182:183] op_sel_hi:[1,0]
	v_pk_mul_f32 v[94:95], v[94:95], v[182:183] op_sel_hi:[1,0]
	v_pk_mul_f32 v[92:93], v[92:93], v[182:183] op_sel_hi:[1,0]

; DI void nsa_ldsfrag(KVFrag& f, const unsigned char* slot, int qi, int quad) {
;   const int krow = 8 * (qi >> 2) + (qi & 3);
; #pragma unroll
;   for (int a = 0; a < 2; ++a) { const unsigned char* kp = slot + (krow + 4 * a) * NSA_KROW + quad * 16; f.k[a][0] = mk8(*(const u32x4*)kp); f.k[a][1] = mk8(*(const u32x4*)(kp + 64)); }
; #pragma unroll
;   for (int dt = 0; dt < 4; ++dt) f.v[dt] = mk8(*(const u32x4*)(slot + 32 * NSA_KROW + (dt * 16 + qi) * NSA_VROW + quad * 16));
; }
; template <int MODE>
; DI void nsa_branch(const bf16_t* __restrict__ Kb, const bf16_t* __restrict__ Vtb, unsigned char* lds, int nb, int t, int cur, unsigned selmask, unsigned umall,
;                    const bf16x8 (&qf)[4][2], f32x4 (&O)[4][4], float (&m)[4], float (&l)[4], bool online) {
;     ...
;     *(u32x4*)(slot1 + ldst) = rb;
;     __syncthreads();
;     rb = *(const u32x4*)(gsrc + (long)kbof(min(n + 3, N - 1)) * gmul);
;     if (won) { KVFrag f; nsa_ldsfrag(f, slot1, qi, quad); nsa_chunk<MODE>(f, j * 64 + 32, t, bit, qf, O, m, l, quad, online); }
.LBB0_737:
	s_min_i32 s14, s54, s55
	s_lshr_b32 s14, s14, 1
	v_add_u32_e32 v116, 0x12600, v161
	s_waitcnt vmcnt(1)
	ds_write_b128 v116, v[108:111]
	s_waitcnt lgkmcnt(0)
	s_barrier
	ds_read_b128 v[136:139], v178
	ds_read_b128 v[140:143], v231
	ds_read_b128 v[144:147], v178 offset:512
	ds_read_b128 v[132:135], v231 offset:512
	ds_read_b128 v[128:131], v179
	ds_read_b128 v[124:127], v179 offset:1024
	ds_read_b128 v[120:123], v179 offset:2048
	ds_read_b128 v[116:119], v179 offset:3072
	v_readlane_b32 s14, v216, s14
	s_andn2_b64 vcc, exec, s[0:1]
	s_lshl_b32 s14, s14, 6
	s_or_b32 s14, s14, 32
	s_ashr_i32 s15, s14, 31
	s_lshl_b64 s[14:15], s[14:15], 7
	v_lshl_add_u64 v[108:109], v[168:169], 0, s[14:15]
	global_load_dwordx4 v[108:111], v[108:109], off
	s_cbranch_vccnz .LBB0_726
	s_and_b64 vcc, exec, s[10:11]
	s_cbranch_vccz .Lmy_nf_s2
	v_readfirstlane_b32 s58, v181
	v_readfirstlane_b32 s59, v160
	s_lshl_b32 s58, s58, 6
	s_add_u32 s60, s58, 63
	s_cmp_le_i32 s60, s59
	s_cbranch_scc0 .Lmy_nf_s2
	v_mov_b32_e32 v226, 0xff800000
	v_cndmask_b32_e64 v218, v226, 0, s[12:13]
	v_cndmask_b32_e64 v219, v226, 0, s[12:13]
	v_cndmask_b32_e64 v220, v226, 0, s[12:13]
	v_cndmask_b32_e64 v221, v226, 0, s[12:13]
	s_branch .Lmy_full_s2

; DI int my_tid() { int t = threadIdx.x; asm volatile("" : "+v"(t)); return t; }
; template <int MODE>
; DI void nsa_branch(const bf16_t* __restrict__ Kb, const bf16_t* __restrict__ Vtb, unsigned char* lds, int nb, int t, int cur, unsigned selmask, unsigned umall,
;                    const bf16x8 (&qf)[4][2], f32x4 (&O)[4][4], float (&m)[4], float (&l)[4], bool online) {
;   const int tid = my_tid(), lane = tid & 63, qi = lane & 15, quad = lane >> 4;
;   const int* blist = (const int*)(lds + NSA_BLIST);
;   const bool isv = tid >= 256;
;   const int t2 = tid & 255;
;   const bf16_t* gsrc = isv ? Vtb + (t2 >> 2) * 32 + (t2 & 3) * 8 : Kb + (long)(t2 >> 3) * 64 + (t2 & 7) * 8;
;   const long gmul = 64;
;   const int ldst = isv ? 32 * NSA_KROW + (t2 >> 2) * NSA_VROW + (t2 & 3) * 16 : (t2 >> 3) * NSA_KROW + (t2 & 7) * 16;
;   unsigned char* slot0 = lds + NSA_SLOT0; unsigned char* slot1 = slot0 + NSA_SLOT;
;   const int N = 2 * nb;
;   auto kbof = [&](int n) { return blist[n >> 1] * 64 + (n & 1) * 32; };
;   u32x4 ra = *(const u32x4*)(gsrc + (long)kbof(0) * gmul), rb = *(const u32x4*)(gsrc + (long)kbof(1) * gmul);
;   *(u32x4*)(slot0 + ldst) = ra;
;   __syncthreads();
; DI void nsa_wave(const Params& p, int layer, int b, int g, int t0, unsigned char* lds, bf16_t* ybase) {
;     ...
;   {
;     const int cur0 = (t0 >> 7) * 2, jlo = cur0 >= 8 ? cur0 - 8 : 0;
;     nb = cur0 + 2 - jlo;
;     if (my_tid() < nb) blist[my_tid()] = jlo + my_tid();
;     __syncthreads();
;     nsa_branch<1>(p.kw() + (long)bg * SEQ * 64, p.vwt() + (long)bg * 64 * SEQ, lds, nb, t, cur, selmask, umall, qf, O, m, l, on_w);
.LBB0_749:
	s_or_b64 exec, exec, s[0:1]
	v_mov_b32_e32 v109, v210
	s_movk_i32 s0, 0xff
	s_waitcnt lgkmcnt(0)
	s_barrier
	v_lshlrev_b32_e32 v217, 2, v228
	v_add_u32_e32 v217, 0x14c20, v217
	ds_read_b32 v216, v217
	s_waitcnt lgkmcnt(0)
	s_nop 0
	v_cmp_lt_i32_e32 vcc, s0, v109
	s_movk_i32 s0, 0x100
	v_cmp_gt_i32_e64 s[0:1], s0, v109
	v_lshlrev_b32_e32 v3, 4, v109
	s_and_saveexec_b64 s[10:11], s[0:1]
	s_xor_b64 s[0:1], exec, s[10:11]
	v_mov_b32_e32 v0, 3
	v_lshrrev_b32_sdwa v0, v0, v109 dst_sel:DWORD dst_unused:UNUSED_PAD src0_sel:DWORD src1_sel:BYTE_0
	v_and_b32_e32 v2, 0x70, v3
	s_movk_i32 s4, 0x90
	v_mad_u32_u24 v2, v0, s4, v2
	s_andn2_saveexec_b64 s[0:1], s[0:1]
	v_mov_b32_e32 v0, 2
	v_lshrrev_b32_sdwa v0, v0, v109 dst_sel:DWORD dst_unused:UNUSED_PAD src0_sel:DWORD src1_sel:BYTE_0
	v_mul_u32_u24_e32 v0, 0x50, v0
	v_and_b32_e32 v2, 48, v3
	s_movk_i32 s4, 0x1200
	v_add3_u32 v2, v0, v2, s4
	s_or_b64 exec, exec, s[0:1]
	v_mov_b32_e32 v44, s30
	ds_read_b32 v44, v44
	v_cndmask_b32_e32 v0, v252, v229, vcc
	v_cndmask_b32_e32 v42, v235, v236, vcc
	v_lshl_add_u64 v[40:41], s[40:41], 0, v[0:1]
	s_lshl_b32 s36, s8, 1
	v_lshlrev_b32_sdwa v0, v238, v109 dst_sel:DWORD dst_unused:UNUSED_PAD src0_sel:DWORD src1_sel:BYTE_0
	s_waitcnt lgkmcnt(0)
	v_readfirstlane_b32 s0, v44
	v_lshl_add_u64 v[40:41], v[40:41], 0, s[36:37]
	v_cndmask_b32_e64 v43, v237, 48, vcc
	v_and_b32_e32 v0, v0, v42
	s_lshl_b32 s0, s0, 6
	v_lshl_add_u64 v[40:41], v[40:41], 0, v[0:1]
	v_and_b32_e32 v0, v3, v43
	s_ashr_i32 s1, s0, 31
	v_lshl_add_u64 v[164:165], v[40:41], 0, v[0:1]
	s_lshl_b64 s[8:9], s[0:1], 7
	s_or_b32 s0, s0, 32
	v_lshl_add_u64 v[40:41], v[164:165], 0, s[8:9]
	s_ashr_i32 s1, s0, 31
	global_load_dwordx4 v[40:43], v[40:41], off
	s_lshl_b64 s[0:1], s[0:1], 7
	v_lshl_add_u64 v[44:45], v[164:165], 0, s[0:1]
	global_load_dwordx4 v[104:107], v[44:45], off
	v_add_u32_e32 v161, 32, v2
	v_mov_b32_e32 v2, v1
	v_mov_b32_e32 v3, v1
	v_add_u32_e32 v166, 0x10000, v161
	v_bfe_u32 v205, v210, 3, 5
	v_bfe_u32 v206, v210, 4, 1
	v_bfe_u32 v207, v210, 6, 2
	v_lshl_or_b32 v206, v207, 1, v206
	v_and_b32_e32 v207, 7, v210
	v_xor_b32_e32 v206, v206, v207
	v_lshlrev_b32_e32 v206, 4, v206
	v_lshl_or_b32 v205, v205, 7, v206
	v_bfe_u32 v206, v210, 2, 6
	v_bfe_u32 v207, v210, 4, 2
	v_sub_u32_e32 v207, 0, v207
	v_and_b32_e32 v207, 3, v207
	v_and_b32_e32 v208, 3, v210
	v_xor_b32_e32 v207, v207, v208
	v_lshlrev_b32_e32 v207, 4, v207
	v_lshl_or_b32 v206, v206, 6, v207
	v_add_u32_e32 v206, 0x1000, v206
	v_bfe_u32 v207, v210, 8, 1
	v_cmp_ne_u32_e64 s[58:59], 0, v207
	s_nop 1
	v_cndmask_b32_e64 v205, v205, v206, s[58:59]
	v_add_u32_e32 v161, 32, v205
	v_add_u32_e32 v166, 0x10000, v161
	v_mov_b32_e32 v155, 0
	v_mov_b32_e32 v0, v1
	v_mov_b64_e32 v[102:103], v[2:3]
	v_mov_b64_e32 v[98:99], v[2:3]
	v_mov_b64_e32 v[94:95], v[2:3]
	v_mov_b64_e32 v[90:91], v[2:3]
	v_mov_b64_e32 v[86:87], v[2:3]
	v_mov_b64_e32 v[82:83], v[2:3]
	v_mov_b64_e32 v[78:79], v[2:3]
	v_mov_b64_e32 v[74:75], v[2:3]
	v_mov_b64_e32 v[70:71], v[2:3]
	v_mov_b64_e32 v[66:67], v[2:3]
	v_mov_b64_e32 v[62:63], v[2:3]
	v_mov_b64_e32 v[58:59], v[2:3]
	v_mov_b64_e32 v[54:55], v[2:3]
	v_mov_b64_e32 v[50:51], v[2:3]
	v_mov_b64_e32 v[46:47], v[2:3]
	v_cmp_lt_i32_e32 vcc, 0, v108
	v_mov_b32_e32 v154, v155
	v_mov_b32_e32 v153, v155
	v_mov_b32_e32 v152, v155
	v_mov_b64_e32 v[100:101], v[0:1]
	v_mov_b64_e32 v[96:97], v[0:1]
	v_mov_b64_e32 v[92:93], v[0:1]
	v_mov_b64_e32 v[88:89], v[0:1]
	v_mov_b64_e32 v[84:85], v[0:1]
	v_mov_b64_e32 v[80:81], v[0:1]
	v_mov_b64_e32 v[76:77], v[0:1]
	v_mov_b64_e32 v[72:73], v[0:1]
	v_mov_b64_e32 v[68:69], v[0:1]
	v_mov_b64_e32 v[64:65], v[0:1]
	v_mov_b64_e32 v[60:61], v[0:1]
	v_mov_b64_e32 v[56:57], v[0:1]
	v_mov_b64_e32 v[52:53], v[0:1]
	v_mov_b64_e32 v[48:49], v[0:1]
	v_mov_b64_e32 v[44:45], v[0:1]
	s_waitcnt vmcnt(1)
	ds_write_b128 v166, v[40:43]
	v_mov_b64_e32 v[42:43], v[2:3]
	v_mov_b64_e32 v[40:41], v[0:1]
	s_waitcnt lgkmcnt(0)
	s_barrier
	s_and_saveexec_b64 s[42:43], vcc
	s_cbranch_execz .LBB0_705
	v_bfe_u32 v2, v109, 4, 2
	v_lshlrev_b32_e32 v3, 1, v109
	v_and_b32_e32 v40, 3, v109
	v_and_or_b32 v3, v3, 24, v40
	v_lshlrev_b32_e32 v40, 4, v2
	v_readlane_b32 s0, v254, 59
	v_and_b32_e32 v0, 15, v109
	v_cmp_lt_f32_e64 s[44:45], s25, v156
	v_add_u32_e32 v43, s0, v40
	v_readlane_b32 s0, v254, 60
	v_add_u32_e32 v41, s35, v40
	v_mul_u32_u24_e32 v42, 0x90, v3
	v_add_u32_e32 v45, s0, v40
	v_readlane_b32 s0, v254, 61
	v_mul_u32_u24_e32 v44, 0x50, v0
	v_lshlrev_b32_e32 v169, 3, v2
	v_add_u32_e32 v40, s0, v40
	v_mov_b32_e32 v2, v1
	v_mov_b32_e32 v3, v1
	v_lshlrev_b32_e32 v167, 1, v108
	v_cndmask_b32_e64 v179, v156, v232, s[44:45]
	v_mov_b32_e32 v0, v1
	v_mov_b32_e32 v152, 0
	v_add_u32_e32 v174, v41, v42
	v_add_u32_e32 v176, v43, v44
	v_add_u32_e32 v177, v45, v42
	v_add_u32_e32 v178, v40, v44
	v_and_b32_e32 v205, 15, v228
	v_lshrrev_b32_e32 v206, 4, v228
	v_bfe_u32 v207, v205, 2, 2
	v_and_b32_e32 v208, 3, v205
	v_lshl_or_b32 v208, v207, 3, v208
	v_bfe_u32 v209, v205, 1, 1
	v_lshl_or_b32 v209, v207, 1, v209
	v_and_b32_e32 v217, 3, v209
	v_xor_b32_e32 v217, v206, v217
	v_lshrrev_b32_e32 v227, 2, v209
	v_lshlrev_b32_e32 v217, 4, v217
	v_lshl_or_b32 v217, v227, 6, v217
	v_lshl_or_b32 v208, v208, 7, v217
	v_xor_b32_e32 v217, 64, v208
	v_sub_u32_e32 v209, 0, v207
	v_and_b32_e32 v209, 3, v209
	v_xor_b32_e32 v209, v206, v209
	v_lshlrev_b32_e32 v209, 4, v209
	v_lshl_or_b32 v205, v205, 6, v209
	v_add_u32_e32 v205, 0x1000, v205
	v_add_u32_e32 v174, 0x10020, v208
	v_add_u32_e32 v230, 0x10020, v217
	v_add_u32_e32 v176, 0x10020, v205
	v_add_u32_e32 v177, 0x12620, v208
	v_add_u32_e32 v231, 0x12620, v217
	v_add_u32_e32 v178, 0x12620, v205
	v_mov_b64_e32 v[42:43], v[2:3]
	v_mov_b64_e32 v[46:47], v[2:3]
	v_mov_b64_e32 v[50:51], v[2:3]
	v_mov_b64_e32 v[54:55], v[2:3]
	v_mov_b64_e32 v[58:59], v[2:3]
	v_mov_b64_e32 v[62:63], v[2:3]
	v_mov_b64_e32 v[66:67], v[2:3]
	v_mov_b64_e32 v[70:71], v[2:3]
	v_mov_b64_e32 v[74:75], v[2:3]
	v_mov_b64_e32 v[78:79], v[2:3]
	v_mov_b64_e32 v[82:83], v[2:3]
	v_mov_b64_e32 v[86:87], v[2:3]
	v_mov_b64_e32 v[90:91], v[2:3]
	v_mov_b64_e32 v[94:95], v[2:3]
	v_mov_b64_e32 v[98:99], v[2:3]
	v_mov_b64_e32 v[102:103], v[2:3]
	v_add_u32_e32 v156, -8, v170
	v_add_u32_e32 v168, -2, v167
	s_mov_b32 s28, 3
	v_add_u32_e32 v171, 0xfffffe00, v160
	v_add_u32_e32 v172, -1, v167
	v_or_b32_e32 v173, 32, v169
	s_mov_b64 s[52:53], 0
	v_mov_b64_e32 v[40:41], v[0:1]
	v_mov_b64_e32 v[44:45], v[0:1]
	v_mov_b64_e32 v[48:49], v[0:1]
	v_mov_b64_e32 v[52:53], v[0:1]
	v_mov_b64_e32 v[56:57], v[0:1]
	v_mov_b64_e32 v[60:61], v[0:1]
	v_mov_b64_e32 v[64:65], v[0:1]
	v_mov_b64_e32 v[68:69], v[0:1]
	v_mov_b64_e32 v[72:73], v[0:1]
	v_mov_b64_e32 v[76:77], v[0:1]
	v_mov_b64_e32 v[80:81], v[0:1]
	v_mov_b64_e32 v[84:85], v[0:1]
	v_mov_b64_e32 v[88:89], v[0:1]
	v_mov_b64_e32 v[92:93], v[0:1]
	v_mov_b64_e32 v[96:97], v[0:1]
	v_mov_b64_e32 v[100:101], v[0:1]
	v_mov_b32_e32 v0, v179
	v_mov_b32_e32 v2, v179
	v_mov_b32_e32 v3, v179
	v_mov_b32_e32 v153, v152
	v_mov_b32_e32 v154, v152
	v_mov_b32_e32 v155, v152
	s_branch .LBB0_757

; template <int MODE>
; DI void nsa_branch(const bf16_t* __restrict__ Kb, const bf16_t* __restrict__ Vtb, unsigned char* lds, int nb, int t, int cur, unsigned selmask, unsigned umall,
;                    const bf16x8 (&qf)[4][2], f32x4 (&O)[4][4], float (&m)[4], float (&l)[4], bool online) {
;     ...
;   auto kbof = [&](int n) { return blist[n >> 1] * 64 + (n & 1) * 32; };
;   u32x4 ra = *(const u32x4*)(gsrc + (long)kbof(0) * gmul), rb = *(const u32x4*)(gsrc + (long)kbof(1) * gmul);
;     ...
;   for (int n = 0; n < N; n += 2) {
;     const int j = blist[n >> 1];
;     const bool won = MODE == 0 ? ((umall >> j) & 1u) != 0 : (j >= cur - 8 && j <= cur);
;     const bool bit = (selmask >> j) & 1u;
;     ra = *(const u32x4*)(gsrc + (long)kbof(min(n + 2, N - 2)) * gmul);
;     if (won) { KVFrag f; nsa_ldsfrag(f, slot0, qi, quad); nsa_chunk<MODE>(f, j * 64, t, bit, qf, O, m, l, quad, online); }
.LBB0_757:
	ds_read_b128 v[132:135], v174
	ds_read_b128 v[136:139], v230
	ds_read_b128 v[140:143], v174 offset:512
	ds_read_b128 v[128:131], v230 offset:512
	ds_read_b128 v[124:127], v176
	ds_read_b128 v[120:123], v176 offset:1024
	ds_read_b128 v[116:119], v176 offset:2048
	s_add_i32 s36, s28, -1
	s_sub_u32 s58, s30, 0x14c20
	s_lshr_b32 s58, s58, 2
	v_readlane_b32 s58, v216, s58
	v_readfirstlane_b32 s59, v168
	s_min_i32 s59, s36, s59
	s_lshr_b32 s59, s59, 1
	v_readlane_b32 s59, v216, s59
	s_nop 1
	v_mov_b32_e32 v180, s58
	v_mov_b32_e32 v108, s59
	v_cmp_ge_i32_e32 vcc, v180, v156
	v_cmp_le_i32_e64 s[0:1], v180, v170
	v_cndmask_b32_e64 v112, 0, 1, s[44:45]
	s_and_b64 s[54:55], vcc, s[0:1]
	v_lshlrev_b32_e32 v108, 6, v108
	v_ashrrev_i32_e32 v109, 31, v108
	v_lshlrev_b64 v[108:109], 7, v[108:109]
	v_lshl_add_u64 v[108:109], v[164:165], 0, v[108:109]
	global_load_dwordx4 v[108:111], v[108:109], off
	v_cmp_ne_u32_e64 s[8:9], 1, v112
	s_and_saveexec_b64 s[56:57], s[54:55]
	s_cbranch_execz .LBB0_767
	s_and_b64 vcc, exec, s[8:9]
	s_cbranch_vccz .Lmy_nf_w1
	v_readfirstlane_b32 s58, v180
	v_readfirstlane_b32 s59, v160
	s_lshl_b32 s58, s58, 6
	s_add_u32 s60, s58, 63
	s_cmp_le_i32 s60, s59
	s_cbranch_scc0 .Lmy_nf_w1
	s_sub_u32 s60, s59, 0x1f1
	s_cmp_gt_i32 s58, s60
	s_cbranch_scc0 .Lmy_nf_w1
	ds_read_b128 v[112:115], v176 offset:3072
	s_branch .Lmy_full_w1
.Lmy_nf_w1:
	v_lshl_or_b32 v181, v180, 6, v169
	v_cmp_le_i32_e32 vcc, v181, v160
	v_cmp_gt_i32_e64 s[0:1], v181, v171
	s_and_b64 s[10:11], vcc, s[0:1]
	v_cmp_lt_i32_e32 vcc, v181, v160
	v_cmp_ge_i32_e64 s[0:1], v181, v171
	v_or_b32_e32 v144, 2, v181
	s_and_b64 s[14:15], vcc, s[0:1]
	v_cmp_le_i32_e32 vcc, v144, v160
	v_cmp_gt_i32_e64 s[0:1], v144, v171
	v_or_b32_e32 v144, 3, v181
	s_and_b64 s[18:19], vcc, s[0:1]
	v_cmp_le_i32_e32 vcc, v144, v160
	v_cmp_gt_i32_e64 s[0:1], v144, v171
	v_or_b32_e32 v144, 4, v181
	s_and_b64 s[46:47], vcc, s[0:1]
	v_cmp_le_i32_e32 vcc, v144, v160
	v_cmp_gt_i32_e64 s[0:1], v144, v171
	v_or_b32_e32 v144, 5, v181
	ds_read_b128 v[112:115], v176 offset:3072
	s_and_b64 s[12:13], vcc, s[0:1]
	v_cmp_le_i32_e32 vcc, v144, v160
	v_cmp_gt_i32_e64 s[0:1], v144, v171
	v_or_b32_e32 v148, 6, v181
	s_and_b64 s[16:17], vcc, s[0:1]
	v_cmp_le_i32_e32 vcc, v148, v160
	v_cmp_gt_i32_e64 s[0:1], v148, v171
	v_or_b32_e32 v181, 7, v181
	s_and_b64 s[48:49], vcc, s[0:1]
	v_cmp_le_i32_e32 vcc, v181, v160
	v_cmp_gt_i32_e64 s[0:1], v181, v171
	s_and_b64 s[50:51], vcc, s[0:1]
	s_and_b64 vcc, exec, s[8:9]
	v_mov_b32_e32 v226, 0xff800000
	v_cndmask_b32_e64 v218, v226, 0, s[10:11]
	v_cndmask_b32_e64 v219, v226, 0, s[14:15]
	v_cndmask_b32_e64 v220, v226, 0, s[18:19]
	v_cndmask_b32_e64 v221, v226, 0, s[46:47]
	v_cndmask_b32_e64 v222, v226, 0, s[12:13]
	v_cndmask_b32_e64 v223, v226, 0, s[16:17]
	v_cndmask_b32_e64 v224, v226, 0, s[48:49]
	v_cndmask_b32_e64 v225, v226, 0, s[50:51]
	s_nop 1
	s_cbranch_vccnz .Lmy_fast_w1
	s_waitcnt lgkmcnt(7)
	v_mfma_f32_16x16x32_bf16 v[144:147], v[132:135], v[8:11], v[218:221]
	s_waitcnt lgkmcnt(6)
	v_mfma_f32_16x16x32_bf16 v[148:151], v[136:139], v[12:15], v[144:147]
	s_waitcnt lgkmcnt(5)
	v_mfma_f32_16x16x32_bf16 v[144:147], v[140:143], v[8:11], v[222:225]
	s_waitcnt lgkmcnt(4)
	v_mfma_f32_16x16x32_bf16 v[144:147], v[128:131], v[12:15], v[144:147]
	s_nop 7
	s_cbranch_vccnz .LBB0_760
	v_mul_f32_e32 v181, 0x3e38aa3b, v148
	v_max_f32_e32 v181, 0xf149f2ca, v181
	v_cndmask_b32_e64 v181, v232, v181, s[10:11]
	v_mul_f32_e32 v182, 0x3e38aa3b, v149
	v_max_f32_e32 v182, v181, v182
	v_cndmask_b32_e64 v181, v181, v182, s[14:15]
	v_mul_f32_e32 v182, 0x3e38aa3b, v150
	v_max_f32_e32 v182, v181, v182
	v_cndmask_b32_e64 v181, v181, v182, s[18:19]
	v_mul_f32_e32 v182, 0x3e38aa3b, v151
	v_max_f32_e32 v182, v181, v182
	v_cndmask_b32_e64 v181, v181, v182, s[46:47]
	v_mul_f32_e32 v182, 0x3e38aa3b, v144
	v_max_f32_e32 v182, v181, v182
	v_cndmask_b32_e64 v181, v181, v182, s[12:13]
	v_mul_f32_e32 v182, 0x3e38aa3b, v145
	v_max_f32_e32 v183, v181, v181
	v_max_f32_e32 v182, v183, v182
	v_cndmask_b32_e64 v181, v181, v182, s[16:17]
	v_mul_f32_e32 v182, 0x3e38aa3b, v146
	v_max_f32_e32 v183, v181, v181
	v_max_f32_e32 v182, v183, v182
	v_cndmask_b32_e64 v181, v181, v182, s[48:49]
	v_mul_f32_e32 v182, 0x3e38aa3b, v147
	v_max_f32_e32 v183, v181, v181
	v_max_f32_e32 v182, v183, v182
	v_cndmask_b32_e64 v181, v181, v182, s[50:51]
	ds_bpermute_b32 v182, v175, v181
	v_max_f32_e32 v181, v181, v181
	s_waitcnt lgkmcnt(0)
	v_max_f32_e32 v182, v182, v182
	v_max_f32_e32 v181, v181, v182
	ds_bpermute_b32 v182, v159, v181
	s_waitcnt lgkmcnt(0)
	v_max3_f32 v181, v3, v181, v182
	v_sub_f32_e32 v3, v3, v181
	v_exp_f32_e32 v182, v3
	v_mov_b32_e32 v3, v181
	v_mul_f32_e32 v155, v155, v182
	v_pk_mul_f32 v[102:103], v[102:103], v[182:183] op_sel_hi:[1,0]
	v_pk_mul_f32 v[100:101], v[100:101], v[182:183] op_sel_hi:[1,0]
	v_pk_mul_f32 v[98:99], v[98:99], v[182:183] op_sel_hi:[1,0]
	v_pk_mul_f32 v[96:97], v[96:97], v[182:183] op_sel_hi:[1,0]
	v_pk_mul_f32 v[94:95], v[94:95], v[182:183] op_sel_hi:[1,0]
	v_pk_mul_f32 v[92:93], v[92:93], v[182:183] op_sel_hi:[1,0]
	v_pk_mul_f32 v[90:91], v[90:91], v[182:183] op_sel_hi:[1,0]
	v_pk_mul_f32 v[88:89], v[88:89], v[182:183] op_sel_hi:[1,0]

; template <int MODE>
; DI void nsa_branch(const bf16_t* __restrict__ Kb, const bf16_t* __restrict__ Vtb, unsigned char* lds, int nb, int t, int cur, unsigned selmask, unsigned umall,
;                    const bf16x8 (&qf)[4][2], f32x4 (&O)[4][4], float (&m)[4], float (&l)[4], bool online) {
;     ...
;     *(u32x4*)(slot1 + ldst) = rb;
;     __syncthreads();
;     rb = *(const u32x4*)(gsrc + (long)kbof(min(n + 3, N - 1)) * gmul);
;     if (won) { KVFrag f; nsa_ldsfrag(f, slot1, qi, quad); nsa_chunk<MODE>(f, j * 64 + 32, t, bit, qf, O, m, l, quad, online); }
.LBB0_767:
	s_or_b64 exec, exec, s[56:57]
	v_add_u32_e32 v112, 0x12600, v161
	s_waitcnt vmcnt(1)
	ds_write_b128 v112, v[104:107]
	v_min_i32_e32 v104, s28, v172
	v_lshlrev_b32_e32 v104, 1, v104
	v_and_b32_e32 v104, -4, v104
	v_add_u32_e32 v104, 32, v104
	v_add_u32_e32 v104, 0x14c00, v104
	s_waitcnt lgkmcnt(0)
	s_barrier
	ds_read_b128 v[132:135], v177
	ds_read_b128 v[136:139], v231
	ds_read_b128 v[140:143], v177 offset:512
	ds_read_b128 v[128:131], v231 offset:512
	ds_read_b128 v[124:127], v178
	ds_read_b128 v[120:123], v178 offset:1024
	ds_read_b128 v[116:119], v178 offset:2048
	ds_read_b128 v[112:115], v178 offset:3072
	v_readfirstlane_b32 s58, v172
	s_min_i32 s58, s28, s58
	s_lshr_b32 s58, s58, 1
	v_readlane_b32 s58, v216, s58
	s_nop 1
	v_mov_b32_e32 v104, s58
	v_lshl_or_b32 v104, v104, 6, 32
	v_ashrrev_i32_e32 v105, 31, v104
	v_lshlrev_b64 v[104:105], 7, v[104:105]
	v_lshl_add_u64 v[104:105], v[164:165], 0, v[104:105]
	global_load_dwordx4 v[104:107], v[104:105], off
	s_and_saveexec_b64 s[56:57], s[54:55]
	s_cbranch_execz .LBB0_756
	s_and_b64 vcc, exec, s[8:9]
	s_cbranch_vccz .Lmy_nf_w2
	v_readfirstlane_b32 s58, v180
	v_readfirstlane_b32 s59, v160
	s_lshl_b32 s58, s58, 6
	s_add_u32 s60, s58, 63
	s_cmp_le_i32 s60, s59
	s_cbranch_scc0 .Lmy_nf_w2
	s_sub_u32 s60, s59, 0x1f1
	s_cmp_gt_i32 s58, s60
	s_cbranch_scc0 .Lmy_nf_w2
	s_branch .Lmy_full_w2
